# FFN2 and WOUT main loops (128x128 tile, K step 64) converted to direct HBM->LDS loads with a swizzled lane-linear LDS image
# speedup vs baseline: 1.0148x; 1.0056x over previous
; DI int TIDX() { int t = threadIdx.x; asm volatile("" : "+v"(t)); return t; }
; #define XCD_LOOP(Mx, ntn) const int xcd_ = BIDX() & 7; for (int u_ = BIDX() >> 3; u_ < (Mx) * (ntn); u_ += (int)(gridDim.x >> 3))
; DI void gemm_tile_deep(const h16* __restrict__ A, int lda, const h16* __restrict__ B, int ldb, int K, f32x16 (&acc)[2][2], h16* sm) {
;   const int tid = TIDX(), lane = tid & 63, w = tid >> 6, wm = w >> 1, wn = w & 1, r = lane & 31, hh = lane >> 5;
;   const unsigned ao = (unsigned)(tid >> 3) * (unsigned)lda + (unsigned)(tid & 7) * 8u;
;   const unsigned bo = (unsigned)(tid >> 3) * (unsigned)ldb + (unsigned)(tid & 7) * 8u;
;   const h16* ag = A;
;   const h16* bg = B;
;   u32x4 ra0[4], rb0[4], ra1[4], rb1[4];
; #pragma unroll
;   for (int i = 0; i < 4; ++i) {
;     ra0[i] = *(const u32x4*)(ag + (ao + (unsigned)i * 32u * (unsigned)lda));
;     rb0[i] = *(const u32x4*)(bg + (bo + (unsigned)i * 32u * (unsigned)ldb));
;   }
;   ag += 64; bg += 64;
; #pragma unroll
;   for (int i = 0; i < 4; ++i) {
;     ra1[i] = *(const u32x4*)(ag + (ao + (unsigned)i * 32u * (unsigned)lda));
;     rb1[i] = *(const u32x4*)(bg + (bo + (unsigned)i * 32u * (unsigned)ldb));
;   }
;   const int nk = K >> 6;
;   const int wofs = (tid >> 3) * LSTR + (tid & 7) * 8;
; DI void phase_gemm_plain(const h16* A, int lda, const h16* Bt, int K, h16* C, int ldc, int mt0, int mt1, int ntn, char* smem) {
;   const int Mx = (mt1 - mt0) >> 3;
;   XCD_LOOP(Mx, ntn) {
;     int mt_, nt_;
;     tile_map(u_, Mx, ntn, xcd_, mt_, nt_);
;     const int m0 = (mt0 + mt_) * 128, n0 = nt_ * 128;
;     f32x16 acc[2][2];
;     zero_acc(acc);
;     gemm_tile_deep(A + (size_t)m0 * lda, lda, Bt + (size_t)n0 * K, K, K, acc, (h16*)smem);
.LBB0_58:
	s_ashr_i32 s8, s15, 31
	s_lshr_b32 s8, s8, 26
	s_add_i32 s8, s15, s8
	s_ashr_i32 s9, s8, 6
	s_lshl_b32 s9, s9, 3
	s_sub_i32 s10, s20, s9
	s_min_i32 s10, s10, 8
	s_abs_i32 s11, s10
	v_cvt_f32_u32_e32 v0, s11
	s_sub_i32 s23, 0, s11
	s_andn2_b32 s8, s8, 63
	s_sub_i32 s8, s15, s8
	v_rcp_iflag_f32_e32 v0, v0
	s_abs_i32 s12, s8
	s_xor_b32 s13, s8, s10
	s_ashr_i32 s13, s13, 31
	v_mul_f32_e32 v0, 0x4f7ffffe, v0
	v_cvt_u32_f32_e32 v0, v0
	v_mov_b32_e32 v18, v203
	v_mov_b32_e32 v7, v1
	v_readfirstlane_b32 s24, v0
	s_mul_i32 s23, s23, s24
	s_mul_hi_u32 s23, s24, s23
	s_add_i32 s24, s24, s23
	s_mul_hi_u32 s23, s12, s24
	s_mul_i32 s24, s23, s11
	s_sub_i32 s12, s12, s24
	s_add_i32 s25, s23, 1
	s_sub_i32 s24, s12, s11
	s_cmp_ge_u32 s12, s11
	s_cselect_b32 s23, s25, s23
	s_cselect_b32 s12, s24, s12
	s_add_i32 s24, s23, 1
	s_cmp_ge_u32 s12, s11
	s_cselect_b32 s11, s24, s23
	s_xor_b32 s11, s11, s13
	s_sub_i32 s12, s11, s13
	s_add_i32 s9, s9, s21
	s_mul_i32 s10, s10, s12
	s_add_i32 s9, s9, s8
	s_sub_i32 s8, s9, s10
	s_lshl_b32 s24, s8, 7
	s_lshl_b32 s23, s12, 7
	s_mul_i32 s8, s8, 0xb0000
	s_mul_hi_i32 s9, s24, 0x1600
	s_add_u32 s10, s18, s8
	s_addc_u32 s11, s19, s9
	s_mul_i32 s12, s12, 0xb0000
	s_add_u32 s8, s16, s12
	v_ashrrev_i32_e32 v19, 3, v18
	s_movk_i32 s12, 0xb00
	v_lshlrev_b32_e32 v2, 3, v18
	v_mul_lo_u32 v0, v19, s12
	v_and_b32_e32 v20, 56, v2
	v_bfe_u32 v21, v18, 4, 3
	v_lshlrev_b32_e32 v21, 3, v21
	v_xor_b32_e32 v20, v20, v21
	v_or_b32_e32 v0, v0, v20
	s_mul_hi_i32 s9, s23, 0x1600
	v_add_u32_e32 v6, 0x42000, v0
	s_addc_u32 s9, s17, s9
	v_add_u32_e32 v2, 0x16000, v0
	v_mov_b32_e32 v3, v1
	v_add_u32_e32 v4, 0x2c000, v0
	v_mov_b32_e32 v5, v1
	s_waitcnt vmcnt(0)
	v_lshlrev_b64 v[146:147], 1, v[6:7]
	v_lshl_add_u64 v[6:7], s[8:9], 0, v[146:147]
	v_lshlrev_b64 v[148:149], 1, v[4:5]
	v_lshlrev_b64 v[150:151], 1, v[2:3]
	v_lshlrev_b64 v[152:153], 1, v[0:1]
	v_lshl_add_u64 v[8:9], s[10:11], 0, v[146:147]
	v_lshl_add_u64 v[4:5], s[8:9], 0, v[148:149]
	v_lshl_add_u64 v[10:11], s[10:11], 0, v[148:149]
	v_lshl_add_u64 v[2:3], s[8:9], 0, v[150:151]
	v_lshl_add_u64 v[12:13], s[10:11], 0, v[150:151]
	v_lshl_add_u64 v[14:15], s[8:9], 0, v[152:153]
	v_lshl_add_u64 v[16:17], s[10:11], 0, v[152:153]
	v_readfirstlane_b32 s38, v203
	s_nop 3
	s_lshr_b32 s38, s38, 6
	s_lshl_b32 s38, s38, 10
	v_and_b32_e32 v140, 31, v203
	v_bfe_u32 v141, v203, 5, 1
	v_bfe_u32 v142, v203, 1, 3
	v_xor_b32_e32 v141, v141, v142
	v_lshlrev_b32_e32 v141, 4, v141
	v_lshl_or_b32 v140, v140, 7, v141
	v_lshrrev_b32_e32 v142, 7, v203
	v_lshl_add_u32 v130, v142, 13, v140
	v_bfe_u32 v142, v203, 6, 1
	v_lshl_add_u32 v134, v142, 13, v140
	v_xor_b32_e32 v131, 0x20, v130
	v_xor_b32_e32 v135, 0x20, v134
	v_xor_b32_e32 v132, 0x40, v130
	v_xor_b32_e32 v136, 0x40, v134
	v_xor_b32_e32 v133, 0x60, v130
	v_xor_b32_e32 v137, 0x60, v134
	s_add_u32 m0, s38, 0x0
	v_lshl_add_u64 v[138:139], s[10:11], 0, v[152:153]
	global_load_lds_dwordx4 v[138:139], off
	s_add_u32 m0, s38, 0x4000
	v_lshl_add_u64 v[138:139], s[8:9], 0, v[152:153]
	global_load_lds_dwordx4 v[138:139], off
	s_add_u32 m0, s38, 0x1000
	v_lshl_add_u64 v[138:139], s[10:11], 0, v[150:151]
	global_load_lds_dwordx4 v[138:139], off
	s_add_u32 m0, s38, 0x5000
	v_lshl_add_u64 v[138:139], s[8:9], 0, v[150:151]
	global_load_lds_dwordx4 v[138:139], off
	s_add_u32 m0, s38, 0x2000
	v_lshl_add_u64 v[138:139], s[10:11], 0, v[148:149]
	global_load_lds_dwordx4 v[138:139], off
	s_add_u32 m0, s38, 0x6000
	v_lshl_add_u64 v[138:139], s[8:9], 0, v[148:149]
	global_load_lds_dwordx4 v[138:139], off
	s_add_u32 m0, s38, 0x3000
	v_lshl_add_u64 v[138:139], s[10:11], 0, v[146:147]
	global_load_lds_dwordx4 v[138:139], off
	s_add_u32 m0, s38, 0x7000
	v_lshl_add_u64 v[138:139], s[8:9], 0, v[146:147]
	global_load_lds_dwordx4 v[138:139], off
	s_add_u32 s8, s8, 0x80
	s_addc_u32 s9, s9, 0
	s_add_u32 s10, s10, 0x80
	s_addc_u32 s11, s11, 0
	v_mov_b32_e32 v2, 0
	s_mov_b32 s22, 0
	v_mov_b32_e32 v3, v2
	v_mov_b32_e32 v4, v2
	v_mov_b32_e32 v5, v2
	v_mov_b32_e32 v6, v2
	v_mov_b32_e32 v7, v2
	v_mov_b32_e32 v8, v2
	v_mov_b32_e32 v9, v2
	v_mov_b32_e32 v10, v2
	v_mov_b32_e32 v11, v2
	v_mov_b32_e32 v12, v2
	v_mov_b32_e32 v13, v2
	v_mov_b32_e32 v14, v2
	v_mov_b32_e32 v15, v2
	v_mov_b32_e32 v16, v2
	v_mov_b32_e32 v17, v2
	v_mov_b32_e32 v18, v2
	v_mov_b32_e32 v19, v2
	v_mov_b32_e32 v20, v2
	v_mov_b32_e32 v21, v2
	v_mov_b32_e32 v22, v2
	v_mov_b32_e32 v23, v2
	v_mov_b32_e32 v24, v2
	v_mov_b32_e32 v25, v2
	v_mov_b32_e32 v26, v2
	v_mov_b32_e32 v27, v2
	v_mov_b32_e32 v28, v2
	v_mov_b32_e32 v29, v2
	v_mov_b32_e32 v30, v2
	v_mov_b32_e32 v31, v2
	v_mov_b32_e32 v32, v2
	v_mov_b32_e32 v33, v2
	v_mov_b32_e32 v34, v2
	v_mov_b32_e32 v35, v2
	v_mov_b32_e32 v36, v2
	v_mov_b32_e32 v37, v2
	v_mov_b32_e32 v38, v2
	v_mov_b32_e32 v39, v2
	v_mov_b32_e32 v40, v2
	v_mov_b32_e32 v41, v2
	v_mov_b32_e32 v42, v2
	v_mov_b32_e32 v43, v2
	v_mov_b32_e32 v44, v2
	v_mov_b32_e32 v45, v2
	v_mov_b32_e32 v46, v2
	v_mov_b32_e32 v47, v2
	v_mov_b32_e32 v48, v2
	v_mov_b32_e32 v49, v2
	v_mov_b32_e32 v50, v2
	v_mov_b32_e32 v51, v2
	v_mov_b32_e32 v52, v2
	v_mov_b32_e32 v53, v2
	v_mov_b32_e32 v54, v2
	v_mov_b32_e32 v55, v2
	v_mov_b32_e32 v56, v2
	v_mov_b32_e32 v57, v2
	v_mov_b32_e32 v58, v2
	v_mov_b32_e32 v59, v2
	v_mov_b32_e32 v60, v2
	v_mov_b32_e32 v61, v2
	v_mov_b32_e32 v62, v2
	v_mov_b32_e32 v63, v2
	v_mov_b32_e32 v64, v2
	v_mov_b32_e32 v65, v2
	s_waitcnt vmcnt(0)
	s_barrier
; DI void gemm_tile_deep(const h16* __restrict__ A, int lda, const h16* __restrict__ B, int ldb, int K, f32x16 (&acc)[2][2], h16* sm) {
;     ...
;   for (int kt = 0; kt < nk; kt += 2) {
;     DEEP_HALF(ra0, rb0, 0, kt)
;     DEEP_HALF(ra1, rb1, 1, kt + 1)
;   }
.Lf2_stage0:
	ds_read_b128 v[66:69], v130 offset:0
	ds_read_b128 v[70:73], v130 offset:4096
	ds_read_b128 v[74:77], v134 offset:16384
	ds_read_b128 v[78:81], v134 offset:20480
	ds_read_b128 v[82:85], v131 offset:0
	ds_read_b128 v[86:89], v131 offset:4096
	ds_read_b128 v[90:93], v135 offset:16384
	ds_read_b128 v[94:97], v135 offset:20480
	ds_read_b128 v[98:101], v132 offset:0
	ds_read_b128 v[102:105], v132 offset:4096
	ds_read_b128 v[106:109], v136 offset:16384
	ds_read_b128 v[110:113], v136 offset:20480
	s_cmp_ge_u32 s22, 43
	s_cbranch_scc1 .Lf2_nl0
	s_add_u32 m0, s38, 0x8000
	v_lshl_add_u64 v[138:139], s[10:11], 0, v[152:153]
	global_load_lds_dwordx4 v[138:139], off
	s_add_u32 m0, s38, 0xc000
	v_lshl_add_u64 v[138:139], s[8:9], 0, v[152:153]
	global_load_lds_dwordx4 v[138:139], off
	s_add_u32 m0, s38, 0x9000
	v_lshl_add_u64 v[138:139], s[10:11], 0, v[150:151]
	global_load_lds_dwordx4 v[138:139], off
	s_add_u32 m0, s38, 0xd000
	v_lshl_add_u64 v[138:139], s[8:9], 0, v[150:151]
	global_load_lds_dwordx4 v[138:139], off
	s_add_u32 m0, s38, 0xa000
	v_lshl_add_u64 v[138:139], s[10:11], 0, v[148:149]
	global_load_lds_dwordx4 v[138:139], off
	s_add_u32 m0, s38, 0xe000
	v_lshl_add_u64 v[138:139], s[8:9], 0, v[148:149]
	global_load_lds_dwordx4 v[138:139], off
	s_add_u32 m0, s38, 0xb000
	v_lshl_add_u64 v[138:139], s[10:11], 0, v[146:147]
	global_load_lds_dwordx4 v[138:139], off
	s_add_u32 m0, s38, 0xf000
	v_lshl_add_u64 v[138:139], s[8:9], 0, v[146:147]
	global_load_lds_dwordx4 v[138:139], off
	s_add_u32 s8, s8, 0x80
	s_addc_u32 s9, s9, 0
	s_add_u32 s10, s10, 0x80
	s_addc_u32 s11, s11, 0
.Lf2_nl0:
	s_waitcnt lgkmcnt(8)
	v_mfma_f32_32x32x16_f16 v[50:65], v[66:69], v[74:77], v[50:65]
	v_mfma_f32_32x32x16_f16 v[34:49], v[66:69], v[78:81], v[34:49]
	v_mfma_f32_32x32x16_f16 v[18:33], v[70:73], v[74:77], v[18:33]
	v_mfma_f32_32x32x16_f16 v[2:17], v[70:73], v[78:81], v[2:17]
	ds_read_b128 v[114:117], v133 offset:0
	ds_read_b128 v[118:121], v133 offset:4096
	ds_read_b128 v[122:125], v137 offset:16384
	ds_read_b128 v[126:129], v137 offset:20480
	s_waitcnt lgkmcnt(8)
	v_mfma_f32_32x32x16_f16 v[50:65], v[82:85], v[90:93], v[50:65]
	v_mfma_f32_32x32x16_f16 v[34:49], v[82:85], v[94:97], v[34:49]
	v_mfma_f32_32x32x16_f16 v[18:33], v[86:89], v[90:93], v[18:33]
	v_mfma_f32_32x32x16_f16 v[2:17], v[86:89], v[94:97], v[2:17]
	s_waitcnt lgkmcnt(4)
	v_mfma_f32_32x32x16_f16 v[50:65], v[98:101], v[106:109], v[50:65]
	v_mfma_f32_32x32x16_f16 v[34:49], v[98:101], v[110:113], v[34:49]
	v_mfma_f32_32x32x16_f16 v[18:33], v[102:105], v[106:109], v[18:33]
	v_mfma_f32_32x32x16_f16 v[2:17], v[102:105], v[110:113], v[2:17]
	s_waitcnt lgkmcnt(0)
	v_mfma_f32_32x32x16_f16 v[50:65], v[114:117], v[122:125], v[50:65]
	v_mfma_f32_32x32x16_f16 v[34:49], v[114:117], v[126:129], v[34:49]
	v_mfma_f32_32x32x16_f16 v[18:33], v[118:121], v[122:125], v[18:33]
	v_mfma_f32_32x32x16_f16 v[2:17], v[118:121], v[126:129], v[2:17]
	s_add_i32 s22, s22, 1
	s_waitcnt vmcnt(0)
	s_barrier
.Lf2_stage1:
	ds_read_b128 v[66:69], v130 offset:32768
	ds_read_b128 v[70:73], v130 offset:36864
	ds_read_b128 v[74:77], v134 offset:49152
	ds_read_b128 v[78:81], v134 offset:53248
	ds_read_b128 v[82:85], v131 offset:32768
	ds_read_b128 v[86:89], v131 offset:36864
	ds_read_b128 v[90:93], v135 offset:49152
	ds_read_b128 v[94:97], v135 offset:53248
	ds_read_b128 v[98:101], v132 offset:32768
	ds_read_b128 v[102:105], v132 offset:36864
	ds_read_b128 v[106:109], v136 offset:49152
	ds_read_b128 v[110:113], v136 offset:53248
	s_cmp_ge_u32 s22, 43
	s_cbranch_scc1 .Lf2_nl1
	s_add_u32 m0, s38, 0x0
	v_lshl_add_u64 v[138:139], s[10:11], 0, v[152:153]
	global_load_lds_dwordx4 v[138:139], off
	s_add_u32 m0, s38, 0x4000
	v_lshl_add_u64 v[138:139], s[8:9], 0, v[152:153]
	global_load_lds_dwordx4 v[138:139], off
	s_add_u32 m0, s38, 0x1000
	v_lshl_add_u64 v[138:139], s[10:11], 0, v[150:151]
	global_load_lds_dwordx4 v[138:139], off
	s_add_u32 m0, s38, 0x5000
	v_lshl_add_u64 v[138:139], s[8:9], 0, v[150:151]
	global_load_lds_dwordx4 v[138:139], off
	s_add_u32 m0, s38, 0x2000
	v_lshl_add_u64 v[138:139], s[10:11], 0, v[148:149]
	global_load_lds_dwordx4 v[138:139], off
	s_add_u32 m0, s38, 0x6000
	v_lshl_add_u64 v[138:139], s[8:9], 0, v[148:149]
	global_load_lds_dwordx4 v[138:139], off
	s_add_u32 m0, s38, 0x3000
	v_lshl_add_u64 v[138:139], s[10:11], 0, v[146:147]
	global_load_lds_dwordx4 v[138:139], off
	s_add_u32 m0, s38, 0x7000
	v_lshl_add_u64 v[138:139], s[8:9], 0, v[146:147]
	global_load_lds_dwordx4 v[138:139], off
	s_add_u32 s8, s8, 0x80
	s_addc_u32 s9, s9, 0
	s_add_u32 s10, s10, 0x80
	s_addc_u32 s11, s11, 0
.Lf2_nl1:
	s_waitcnt lgkmcnt(8)
	v_mfma_f32_32x32x16_f16 v[50:65], v[66:69], v[74:77], v[50:65]
	v_mfma_f32_32x32x16_f16 v[34:49], v[66:69], v[78:81], v[34:49]
	v_mfma_f32_32x32x16_f16 v[18:33], v[70:73], v[74:77], v[18:33]
	v_mfma_f32_32x32x16_f16 v[2:17], v[70:73], v[78:81], v[2:17]
	ds_read_b128 v[114:117], v133 offset:32768
	ds_read_b128 v[118:121], v133 offset:36864
	ds_read_b128 v[122:125], v137 offset:49152
	ds_read_b128 v[126:129], v137 offset:53248
	s_waitcnt lgkmcnt(8)
	v_mfma_f32_32x32x16_f16 v[50:65], v[82:85], v[90:93], v[50:65]
	v_mfma_f32_32x32x16_f16 v[34:49], v[82:85], v[94:97], v[34:49]
	v_mfma_f32_32x32x16_f16 v[18:33], v[86:89], v[90:93], v[18:33]
	v_mfma_f32_32x32x16_f16 v[2:17], v[86:89], v[94:97], v[2:17]
	s_waitcnt lgkmcnt(4)
	v_mfma_f32_32x32x16_f16 v[50:65], v[98:101], v[106:109], v[50:65]
	v_mfma_f32_32x32x16_f16 v[34:49], v[98:101], v[110:113], v[34:49]
	v_mfma_f32_32x32x16_f16 v[18:33], v[102:105], v[106:109], v[18:33]
	v_mfma_f32_32x32x16_f16 v[2:17], v[102:105], v[110:113], v[2:17]
	s_waitcnt lgkmcnt(0)
	v_mfma_f32_32x32x16_f16 v[50:65], v[114:117], v[122:125], v[50:65]
	v_mfma_f32_32x32x16_f16 v[34:49], v[114:117], v[126:129], v[34:49]
	v_mfma_f32_32x32x16_f16 v[18:33], v[118:121], v[122:125], v[18:33]
	v_mfma_f32_32x32x16_f16 v[2:17], v[118:121], v[126:129], v[2:17]
	s_add_i32 s22, s22, 1
	s_cmp_ge_u32 s22, 44
	s_cbranch_scc1 .LBB0_57
	s_waitcnt vmcnt(0)
	s_barrier
	s_branch .Lf2_stage0

; DI int TIDX() { int t = threadIdx.x; asm volatile("" : "+v"(t)); return t; }
; DI void gemm_tile_deep(const h16* __restrict__ A, int lda, const h16* __restrict__ B, int ldb, int K, f32x16 (&acc)[2][2], h16* sm) {
;   const int tid = TIDX(), lane = tid & 63, w = tid >> 6, wm = w >> 1, wn = w & 1, r = lane & 31, hh = lane >> 5;
;   const unsigned ao = (unsigned)(tid >> 3) * (unsigned)lda + (unsigned)(tid & 7) * 8u;
;   const unsigned bo = (unsigned)(tid >> 3) * (unsigned)ldb + (unsigned)(tid & 7) * 8u;
;   const h16* ag = A;
;   const h16* bg = B;
;   u32x4 ra0[4], rb0[4], ra1[4], rb1[4];
; #pragma unroll
;   for (int i = 0; i < 4; ++i) {
;     ra0[i] = *(const u32x4*)(ag + (ao + (unsigned)i * 32u * (unsigned)lda));
;     rb0[i] = *(const u32x4*)(bg + (bo + (unsigned)i * 32u * (unsigned)ldb));
;   }
;   ag += 64; bg += 64;
; #pragma unroll
;   for (int i = 0; i < 4; ++i) {
;     ra1[i] = *(const u32x4*)(ag + (ao + (unsigned)i * 32u * (unsigned)lda));
;     rb1[i] = *(const u32x4*)(bg + (bo + (unsigned)i * 32u * (unsigned)ldb));
;   }
;   const int nk = K >> 6;
;   const int wofs = (tid >> 3) * LSTR + (tid & 7) * 8;
.LBB0_91:
	s_ashr_i32 s4, s15, 31
	s_lshr_b32 s4, s4, 26
	s_add_i32 s4, s15, s4
	s_ashr_i32 s5, s4, 6
	s_lshl_b32 s5, s5, 3
	s_sub_i32 s6, s20, s5
	s_min_i32 s6, s6, 8
	s_abs_i32 s7, s6
	v_cvt_f32_u32_e32 v0, s7
	s_sub_i32 s10, 0, s7
	s_andn2_b32 s4, s4, 63
	s_sub_i32 s4, s15, s4
	v_rcp_iflag_f32_e32 v0, v0
	s_abs_i32 s8, s4
	s_xor_b32 s9, s4, s6
	s_ashr_i32 s9, s9, 31
	v_mul_f32_e32 v0, 0x4f7ffffe, v0
	v_cvt_u32_f32_e32 v0, v0
	v_mov_b32_e32 v18, v203
	v_mov_b32_e32 v7, v1
	v_readfirstlane_b32 s11, v0
	s_mul_i32 s10, s10, s11
	s_mul_hi_u32 s10, s11, s10
	s_add_i32 s11, s11, s10
	s_mul_hi_u32 s10, s8, s11
	s_mul_i32 s11, s10, s7
	s_sub_i32 s8, s8, s11
	s_add_i32 s12, s10, 1
	s_sub_i32 s11, s8, s7
	s_cmp_ge_u32 s8, s7
	s_cselect_b32 s10, s12, s10
	s_cselect_b32 s8, s11, s8
	s_add_i32 s11, s10, 1
	s_cmp_ge_u32 s8, s7
	s_cselect_b32 s7, s11, s10
	s_xor_b32 s7, s7, s9
	s_sub_i32 s7, s7, s9
	s_add_i32 s5, s5, s21
	s_mul_i32 s6, s6, s7
	s_add_i32 s5, s5, s4
	s_sub_i32 s4, s5, s6
	s_lshl_b32 s6, s4, 7
	s_lshl_b32 s4, s7, 7
	s_ashr_i32 s7, s6, 31
	s_lshl_b64 s[8:9], s[6:7], 11
	s_add_u32 s10, s16, s8
	v_lshlrev_b32_e32 v0, 3, v18
	s_addc_u32 s11, s17, s9
	s_ashr_i32 s5, s4, 31
	v_ashrrev_i32_e32 v19, 3, v18
	v_and_b32_e32 v20, 56, v0
	v_bfe_u32 v21, v18, 4, 3
	v_lshlrev_b32_e32 v21, 3, v21
	v_xor_b32_e32 v20, v20, v21
	s_lshl_b64 s[8:9], s[4:5], 11
	v_lshl_or_b32 v0, v19, 10, v20
	s_add_u32 s8, s18, s8
	v_add_u32_e32 v6, 0x18000, v0
	s_addc_u32 s9, s19, s9
	v_add_u32_e32 v2, 0x8000, v0
	v_mov_b32_e32 v3, v1
	v_add_u32_e32 v4, 0x10000, v0
	v_mov_b32_e32 v5, v1
	s_waitcnt vmcnt(0)
	v_lshlrev_b64 v[146:147], 1, v[6:7]
	v_lshl_add_u64 v[6:7], s[8:9], 0, v[146:147]
	v_lshlrev_b64 v[148:149], 1, v[4:5]
	v_lshlrev_b64 v[150:151], 1, v[2:3]
	v_lshlrev_b64 v[152:153], 1, v[0:1]
	v_lshl_add_u64 v[8:9], s[10:11], 0, v[146:147]
	v_lshl_add_u64 v[4:5], s[8:9], 0, v[148:149]
	v_lshl_add_u64 v[10:11], s[10:11], 0, v[148:149]
	v_lshl_add_u64 v[2:3], s[8:9], 0, v[150:151]
	v_lshl_add_u64 v[12:13], s[10:11], 0, v[150:151]
	v_lshl_add_u64 v[14:15], s[8:9], 0, v[152:153]
	v_lshl_add_u64 v[16:17], s[10:11], 0, v[152:153]
	v_readfirstlane_b32 s38, v203
	s_nop 3
	s_lshr_b32 s38, s38, 6
	s_lshl_b32 s38, s38, 10
	v_and_b32_e32 v140, 31, v203
	v_bfe_u32 v141, v203, 5, 1
	v_bfe_u32 v142, v203, 1, 3
	v_xor_b32_e32 v141, v141, v142
	v_lshlrev_b32_e32 v141, 4, v141
	v_lshl_or_b32 v140, v140, 7, v141
	v_lshrrev_b32_e32 v142, 7, v203
	v_lshl_add_u32 v130, v142, 13, v140
	v_bfe_u32 v142, v203, 6, 1
	v_lshl_add_u32 v134, v142, 13, v140
	v_xor_b32_e32 v131, 0x20, v130
	v_xor_b32_e32 v135, 0x20, v134
	v_xor_b32_e32 v132, 0x40, v130
	v_xor_b32_e32 v136, 0x40, v134
	v_xor_b32_e32 v133, 0x60, v130
	v_xor_b32_e32 v137, 0x60, v134
	s_add_u32 m0, s38, 0x0
	v_lshl_add_u64 v[138:139], s[10:11], 0, v[152:153]
	global_load_lds_dwordx4 v[138:139], off
	s_add_u32 m0, s38, 0x4000
	v_lshl_add_u64 v[138:139], s[8:9], 0, v[152:153]
	global_load_lds_dwordx4 v[138:139], off
	s_add_u32 m0, s38, 0x1000
	v_lshl_add_u64 v[138:139], s[10:11], 0, v[150:151]
	global_load_lds_dwordx4 v[138:139], off
	s_add_u32 m0, s38, 0x5000
	v_lshl_add_u64 v[138:139], s[8:9], 0, v[150:151]
	global_load_lds_dwordx4 v[138:139], off
	s_add_u32 m0, s38, 0x2000
	v_lshl_add_u64 v[138:139], s[10:11], 0, v[148:149]
	global_load_lds_dwordx4 v[138:139], off
	s_add_u32 m0, s38, 0x6000
	v_lshl_add_u64 v[138:139], s[8:9], 0, v[148:149]
	global_load_lds_dwordx4 v[138:139], off
	s_add_u32 m0, s38, 0x3000
	v_lshl_add_u64 v[138:139], s[10:11], 0, v[146:147]
	global_load_lds_dwordx4 v[138:139], off
	s_add_u32 m0, s38, 0x7000
	v_lshl_add_u64 v[138:139], s[8:9], 0, v[146:147]
	global_load_lds_dwordx4 v[138:139], off
	s_add_u32 s8, s8, 0x80
	s_addc_u32 s9, s9, 0
	s_add_u32 s10, s10, 0x80
	s_addc_u32 s11, s11, 0
	v_mov_b32_e32 v2, 0
	s_mov_b32 s22, 0
	v_mov_b32_e32 v3, v2
	v_mov_b32_e32 v4, v2
	v_mov_b32_e32 v5, v2
	v_mov_b32_e32 v6, v2
	v_mov_b32_e32 v7, v2
	v_mov_b32_e32 v8, v2
	v_mov_b32_e32 v9, v2
	v_mov_b32_e32 v10, v2
	v_mov_b32_e32 v11, v2
	v_mov_b32_e32 v12, v2
	v_mov_b32_e32 v13, v2
	v_mov_b32_e32 v14, v2
	v_mov_b32_e32 v15, v2
	v_mov_b32_e32 v16, v2
	v_mov_b32_e32 v17, v2
	v_mov_b32_e32 v18, v2
	v_mov_b32_e32 v19, v2
	v_mov_b32_e32 v20, v2
	v_mov_b32_e32 v21, v2
	v_mov_b32_e32 v22, v2
	v_mov_b32_e32 v23, v2
	v_mov_b32_e32 v24, v2
	v_mov_b32_e32 v25, v2
	v_mov_b32_e32 v26, v2
	v_mov_b32_e32 v27, v2
	v_mov_b32_e32 v28, v2
	v_mov_b32_e32 v29, v2
	v_mov_b32_e32 v30, v2
	v_mov_b32_e32 v31, v2
	v_mov_b32_e32 v32, v2
	v_mov_b32_e32 v33, v2
	v_mov_b32_e32 v34, v2
	v_mov_b32_e32 v35, v2
	v_mov_b32_e32 v36, v2
	v_mov_b32_e32 v37, v2
	v_mov_b32_e32 v38, v2
	v_mov_b32_e32 v39, v2
	v_mov_b32_e32 v40, v2
	v_mov_b32_e32 v41, v2
	v_mov_b32_e32 v42, v2
	v_mov_b32_e32 v43, v2
	v_mov_b32_e32 v44, v2
	v_mov_b32_e32 v45, v2
	v_mov_b32_e32 v46, v2
	v_mov_b32_e32 v47, v2
	v_mov_b32_e32 v48, v2
	v_mov_b32_e32 v49, v2
	v_mov_b32_e32 v50, v2
	v_mov_b32_e32 v51, v2
	v_mov_b32_e32 v52, v2
	v_mov_b32_e32 v53, v2
	v_mov_b32_e32 v54, v2
	v_mov_b32_e32 v55, v2
	v_mov_b32_e32 v56, v2
	v_mov_b32_e32 v57, v2
	v_mov_b32_e32 v58, v2
	v_mov_b32_e32 v59, v2
	v_mov_b32_e32 v60, v2
	v_mov_b32_e32 v61, v2
	v_mov_b32_e32 v62, v2
	v_mov_b32_e32 v63, v2
	v_mov_b32_e32 v64, v2
	v_mov_b32_e32 v65, v2
	s_waitcnt vmcnt(0)
	s_barrier
.Lwo_stage0:
	ds_read_b128 v[66:69], v130 offset:0
	ds_read_b128 v[70:73], v130 offset:4096
	ds_read_b128 v[74:77], v134 offset:16384
	ds_read_b128 v[78:81], v134 offset:20480
	ds_read_b128 v[82:85], v131 offset:0
	ds_read_b128 v[86:89], v131 offset:4096
	ds_read_b128 v[90:93], v135 offset:16384
	ds_read_b128 v[94:97], v135 offset:20480
	ds_read_b128 v[98:101], v132 offset:0
	ds_read_b128 v[102:105], v132 offset:4096
	ds_read_b128 v[106:109], v136 offset:16384
	ds_read_b128 v[110:113], v136 offset:20480
	s_cmp_ge_u32 s22, 15
	s_cbranch_scc1 .Lwo_nl0
	s_add_u32 m0, s38, 0x8000
	v_lshl_add_u64 v[138:139], s[10:11], 0, v[152:153]
	global_load_lds_dwordx4 v[138:139], off
	s_add_u32 m0, s38, 0xc000
	v_lshl_add_u64 v[138:139], s[8:9], 0, v[152:153]
	global_load_lds_dwordx4 v[138:139], off
	s_add_u32 m0, s38, 0x9000
	v_lshl_add_u64 v[138:139], s[10:11], 0, v[150:151]
	global_load_lds_dwordx4 v[138:139], off
	s_add_u32 m0, s38, 0xd000
	v_lshl_add_u64 v[138:139], s[8:9], 0, v[150:151]
	global_load_lds_dwordx4 v[138:139], off
	s_add_u32 m0, s38, 0xa000
	v_lshl_add_u64 v[138:139], s[10:11], 0, v[148:149]
	global_load_lds_dwordx4 v[138:139], off
	s_add_u32 m0, s38, 0xe000
	v_lshl_add_u64 v[138:139], s[8:9], 0, v[148:149]
	global_load_lds_dwordx4 v[138:139], off
	s_add_u32 m0, s38, 0xb000
	v_lshl_add_u64 v[138:139], s[10:11], 0, v[146:147]
	global_load_lds_dwordx4 v[138:139], off
	s_add_u32 m0, s38, 0xf000
	v_lshl_add_u64 v[138:139], s[8:9], 0, v[146:147]
	global_load_lds_dwordx4 v[138:139], off
	s_add_u32 s8, s8, 0x80
	s_addc_u32 s9, s9, 0
	s_add_u32 s10, s10, 0x80
	s_addc_u32 s11, s11, 0

; DI void gemm_tile_deep(const h16* __restrict__ A, int lda, const h16* __restrict__ B, int ldb, int K, f32x16 (&acc)[2][2], h16* sm) {
;     ...
;   for (int kt = 0; kt < nk; kt += 2) {
;     DEEP_HALF(ra0, rb0, 0, kt)
;     DEEP_HALF(ra1, rb1, 1, kt + 1)
;   }
.Lwo_stage1:
	ds_read_b128 v[66:69], v130 offset:32768
	ds_read_b128 v[70:73], v130 offset:36864
	ds_read_b128 v[74:77], v134 offset:49152
	ds_read_b128 v[78:81], v134 offset:53248
	ds_read_b128 v[82:85], v131 offset:32768
	ds_read_b128 v[86:89], v131 offset:36864
	ds_read_b128 v[90:93], v135 offset:49152
	ds_read_b128 v[94:97], v135 offset:53248
	ds_read_b128 v[98:101], v132 offset:32768
	ds_read_b128 v[102:105], v132 offset:36864
	ds_read_b128 v[106:109], v136 offset:49152
	ds_read_b128 v[110:113], v136 offset:53248
	s_cmp_ge_u32 s22, 15
	s_cbranch_scc1 .Lwo_nl1
	s_add_u32 m0, s38, 0x0
	v_lshl_add_u64 v[138:139], s[10:11], 0, v[152:153]
	global_load_lds_dwordx4 v[138:139], off
	s_add_u32 m0, s38, 0x4000
	v_lshl_add_u64 v[138:139], s[8:9], 0, v[152:153]
	global_load_lds_dwordx4 v[138:139], off
	s_add_u32 m0, s38, 0x1000
	v_lshl_add_u64 v[138:139], s[10:11], 0, v[150:151]
	global_load_lds_dwordx4 v[138:139], off
	s_add_u32 m0, s38, 0x5000
	v_lshl_add_u64 v[138:139], s[8:9], 0, v[150:151]
	global_load_lds_dwordx4 v[138:139], off
	s_add_u32 m0, s38, 0x2000
	v_lshl_add_u64 v[138:139], s[10:11], 0, v[148:149]
	global_load_lds_dwordx4 v[138:139], off
	s_add_u32 m0, s38, 0x6000
	v_lshl_add_u64 v[138:139], s[8:9], 0, v[148:149]
	global_load_lds_dwordx4 v[138:139], off
	s_add_u32 m0, s38, 0x3000
	v_lshl_add_u64 v[138:139], s[10:11], 0, v[146:147]
	global_load_lds_dwordx4 v[138:139], off
	s_add_u32 m0, s38, 0x7000
	v_lshl_add_u64 v[138:139], s[8:9], 0, v[146:147]
	global_load_lds_dwordx4 v[138:139], off
	s_add_u32 s8, s8, 0x80
	s_addc_u32 s9, s9, 0
	s_add_u32 s10, s10, 0x80
	s_addc_u32 s11, s11, 0
.Lwo_nl1:
	s_waitcnt lgkmcnt(8)
	v_mfma_f32_32x32x16_f16 v[50:65], v[66:69], v[74:77], v[50:65]
	v_mfma_f32_32x32x16_f16 v[34:49], v[66:69], v[78:81], v[34:49]
	v_mfma_f32_32x32x16_f16 v[18:33], v[70:73], v[74:77], v[18:33]
	v_mfma_f32_32x32x16_f16 v[2:17], v[70:73], v[78:81], v[2:17]
	ds_read_b128 v[114:117], v133 offset:32768
	ds_read_b128 v[118:121], v133 offset:36864
	ds_read_b128 v[122:125], v137 offset:49152
	ds_read_b128 v[126:129], v137 offset:53248
	s_waitcnt lgkmcnt(8)
	v_mfma_f32_32x32x16_f16 v[50:65], v[82:85], v[90:93], v[50:65]
	v_mfma_f32_32x32x16_f16 v[34:49], v[82:85], v[94:97], v[34:49]
	v_mfma_f32_32x32x16_f16 v[18:33], v[86:89], v[90:93], v[18:33]
	v_mfma_f32_32x32x16_f16 v[2:17], v[86:89], v[94:97], v[2:17]
	s_waitcnt lgkmcnt(4)
	v_mfma_f32_32x32x16_f16 v[50:65], v[98:101], v[106:109], v[50:65]
	v_mfma_f32_32x32x16_f16 v[34:49], v[98:101], v[110:113], v[34:49]
	v_mfma_f32_32x32x16_f16 v[18:33], v[102:105], v[106:109], v[18:33]
	v_mfma_f32_32x32x16_f16 v[2:17], v[102:105], v[110:113], v[2:17]
	s_waitcnt lgkmcnt(0)
	v_mfma_f32_32x32x16_f16 v[50:65], v[114:117], v[122:125], v[50:65]
	v_mfma_f32_32x32x16_f16 v[34:49], v[114:117], v[126:129], v[34:49]
	v_mfma_f32_32x32x16_f16 v[18:33], v[118:121], v[122:125], v[18:33]
	v_mfma_f32_32x32x16_f16 v[2:17], v[118:121], v[126:129], v[2:17]
	s_add_i32 s22, s22, 1
	s_cmp_ge_u32 s22, 16
	s_cbranch_scc1 .LBB0_90
	s_waitcnt vmcnt(0)
	s_barrier
	s_branch .Lwo_stage0
